# in-projection loop: last two DMA issues of the heavy load segments moved into the following MFMA segment
# baseline (speedup 1.0000x reference)
; #define PG8_STAGE(bufoff, gbase, voff) do { _Pragma("unroll") for (int _i = 0; _i < 2; ++_i) \
;         __builtin_amdgcn_global_load_lds((const unsigned*)((const char*)(gbase) + (voff)[_i]), (LAS unsigned*)(lds + (bufoff) + ldsw + _i * 8192), 16, 0, 0); } while (0)
; #define PG8_LDA(dst, b, h) do { _Pragma("unroll") for (int m = 0; m < 4; ++m) _Pragma("unroll") for (int k = 0; k < 2; ++k) dst[m][k] = *(const LAS bf16x8*)(lds + PG8_SA(b, h) + aoff + m * 2048 + k * 1024); } while (0)
; #define PG8_LDB(dst, b, h) do { _Pragma("unroll") for (int n = 0; n < 2; ++n) _Pragma("unroll") for (int k = 0; k < 2; ++k) dst[n][k] = *(const LAS bf16x8*)(lds + PG8_SB(b, h) + boff + n * 2048 + k * 1024); } while (0)
; #define PG8_MMA(ai, bj, At, Bt) do { __builtin_amdgcn_s_setprio(1); _Pragma("unroll") for (int m = 0; m < 4; ++m) _Pragma("unroll") for (int n = 0; n < 2; ++n) _Pragma("unroll") for (int k = 0; k < 2; ++k) \
;         acc[ai][bj][m][n] = __builtin_amdgcn_mfma_f32_16x16x32_bf16(Bt[n][k], At[m][k], acc[ai][bj][m][n], 0, 0, 0); __builtin_amdgcn_s_setprio(0); } while (0)
; #define PG8_WAIT_V(n) asm volatile("s_waitcnt vmcnt(" #n ")" ::: "memory")
; #define PG8_WAIT_L(n) asm volatile("s_waitcnt lgkmcnt(" #n ")" ::: "memory")
; #define PG8_BAR __builtin_amdgcn_s_barrier()
; #define PG8_SCHED __builtin_amdgcn_sched_barrier(0)
; template <class Epi, class Sched>
; __device__ __forceinline__ void gemm_phase(LAS unsigned char* lds, const Gemm g, const Sched& S, const Epi& E, const int tid) {
;     ...
;             PG8_LDB(B0, 0, 0); PG8_LDB(B1, 0, 1); PG8_SCHED; PG8_LDA(At, 0, 0); PG8_STAGE(PG8_SA(1, 1), a1 + hstepA, voffA);
;             PG8_WAIT_V(8); PG8_WAIT_L(0); PG8_BAR; PG8_MMA(0, 0, At, B0); PG8_MMA(0, 1, At, B1); PG8_BAR; PG8_SCHED;
;             PG8_LDA(At, 0, 1); PG8_STAGE(PG8_SB(0, 0), b2, voffB); PG8_STAGE(PG8_SB(0, 1), b2 + hstepB, voffB); PG8_STAGE(PG8_SA(0, 0), a2, voffA);
;             PG8_WAIT_V(8); PG8_WAIT_L(0); PG8_BAR; PG8_MMA(1, 0, At, B0); PG8_MMA(1, 1, At, B1); PG8_BAR; PG8_SCHED;
.LBB0_347:
	s_add_u32 s24, s2, 0xfff80080
	s_addc_u32 s26, s3, -1
	s_add_i32 s31, 0, 0x10000
	s_cmp_eq_u32 s22, 28
	s_cselect_b32 s49, s15, s26
	s_cselect_b32 s48, s16, s24
	s_cselect_b32 s39, s11, s21
	s_cselect_b32 s38, s19, s20
	s_add_i32 s24, 0, 0x14000
	v_add_u32_e32 v140, s31, v158
	v_add_u32_e32 v154, s24, v158
	ds_read_b128 v[128:131], v140
	ds_read_b128 v[132:135], v140 offset:1024
	ds_read_b128 v[136:139], v140 offset:2048
	ds_read_b128 v[140:143], v140 offset:3072
	ds_read_b128 v[160:163], v154
	ds_read_b128 v[164:167], v154 offset:1024
	ds_read_b128 v[168:171], v154 offset:2048
	ds_read_b128 v[172:175], v154 offset:3072
	v_lshl_add_u64 v[154:155], s[2:3], 0, v[150:151]
	s_add_i32 m0, s45, 0xc000
	ds_read_b128 v[176:179], v159
	ds_read_b128 v[180:183], v159 offset:1024
	ds_read_b128 v[184:187], v159 offset:2048
	ds_read_b128 v[188:191], v159 offset:3072
	ds_read_b128 v[202:205], v159 offset:4096
	ds_read_b128 v[206:209], v159 offset:5120
	ds_read_b128 v[210:213], v159 offset:6144
	ds_read_b128 v[214:217], v159 offset:7168
	global_load_lds_dwordx4 v[154:155], off
	v_lshl_add_u64 v[154:155], s[2:3], 0, v[152:153]
	s_add_i32 m0, s45, 0xe000
	s_nop 0
	global_load_lds_dwordx4 v[154:155], off
	s_waitcnt vmcnt(8)
	s_waitcnt lgkmcnt(0)
	s_barrier
	s_waitcnt lgkmcnt(0)
	v_mfma_f32_16x16x32_bf16 v[124:127], v[128:131], v[176:179], v[124:127]
	v_mfma_f32_16x16x32_bf16 v[120:123], v[136:139], v[176:179], v[120:123]
	v_mfma_f32_16x16x32_bf16 v[108:111], v[128:131], v[184:187], v[108:111]
	v_lshl_add_u64 v[154:155], s[38:39], 0, v[192:193]
	v_mfma_f32_16x16x32_bf16 v[104:107], v[136:139], v[184:187], v[104:107]
	v_mfma_f32_16x16x32_bf16 v[92:95], v[128:131], v[202:205], v[92:95]
	v_mfma_f32_16x16x32_bf16 v[88:91], v[136:139], v[202:205], v[88:91]
	s_add_u32 s64, s38, 0x80000
	s_addc_u32 s65, s39, 0
	v_mfma_f32_16x16x32_bf16 v[76:79], v[128:131], v[210:213], v[76:79]
	v_mfma_f32_16x16x32_bf16 v[72:75], v[136:139], v[210:213], v[72:75]
	v_mfma_f32_16x16x32_bf16 v[124:127], v[132:135], v[180:183], v[124:127]
	v_lshl_add_u64 v[218:219], s[38:39], 0, v[148:149]
	v_mfma_f32_16x16x32_bf16 v[120:123], v[140:143], v[180:183], v[120:123]
	v_mfma_f32_16x16x32_bf16 v[108:111], v[132:135], v[188:191], v[108:111]
	v_mfma_f32_16x16x32_bf16 v[104:107], v[140:143], v[188:191], v[104:107]
	v_mfma_f32_16x16x32_bf16 v[92:95], v[132:135], v[206:209], v[92:95]
	v_lshl_add_u64 v[236:237], s[64:65], 0, v[192:193]
	v_mfma_f32_16x16x32_bf16 v[88:91], v[140:143], v[206:209], v[88:91]
	v_mfma_f32_16x16x32_bf16 v[76:79], v[132:135], v[214:217], v[76:79]
	v_mfma_f32_16x16x32_bf16 v[72:75], v[140:143], v[214:217], v[72:75]
	v_mfma_f32_16x16x32_bf16 v[116:119], v[160:163], v[176:179], v[116:119]
	v_mfma_f32_16x16x32_bf16 v[112:115], v[168:171], v[176:179], v[112:115]
	v_lshl_add_u64 v[238:239], s[64:65], 0, v[148:149]
	v_mfma_f32_16x16x32_bf16 v[100:103], v[160:163], v[184:187], v[100:103]
	v_mfma_f32_16x16x32_bf16 v[96:99], v[168:171], v[184:187], v[96:99]
	v_mfma_f32_16x16x32_bf16 v[84:87], v[160:163], v[202:205], v[84:87]
	v_mfma_f32_16x16x32_bf16 v[80:83], v[168:171], v[202:205], v[80:83]
	v_lshl_add_u64 v[220:221], s[48:49], 0, v[144:145]
	v_mfma_f32_16x16x32_bf16 v[68:71], v[160:163], v[210:213], v[68:71]
	v_mfma_f32_16x16x32_bf16 v[64:67], v[168:171], v[210:213], v[64:67]
	v_mfma_f32_16x16x32_bf16 v[116:119], v[164:167], v[180:183], v[116:119]
	v_mfma_f32_16x16x32_bf16 v[112:115], v[172:175], v[180:183], v[112:115]
	v_lshl_add_u64 v[222:223], s[48:49], 0, v[146:147]
	v_mfma_f32_16x16x32_bf16 v[100:103], v[164:167], v[188:191], v[100:103]
	v_mfma_f32_16x16x32_bf16 v[96:99], v[172:175], v[188:191], v[96:99]
	v_mfma_f32_16x16x32_bf16 v[84:87], v[164:167], v[206:209], v[84:87]
	v_mfma_f32_16x16x32_bf16 v[80:83], v[172:175], v[206:209], v[80:83]
	v_mfma_f32_16x16x32_bf16 v[68:71], v[164:167], v[214:217], v[68:71]
	v_mfma_f32_16x16x32_bf16 v[64:67], v[172:175], v[214:217], v[64:67]
	s_barrier
	s_add_i32 s26, s31, s25
	s_mov_b32 m0, s26
	ds_read_b128 v[176:179], v159 offset:16384
	ds_read_b128 v[180:183], v159 offset:17408
	ds_read_b128 v[184:187], v159 offset:18432
	ds_read_b128 v[188:191], v159 offset:19456
	ds_read_b128 v[202:205], v159 offset:20480
	ds_read_b128 v[206:209], v159 offset:21504
	ds_read_b128 v[210:213], v159 offset:22528
	ds_read_b128 v[214:217], v159 offset:23552
	global_load_lds_dwordx4 v[154:155], off
	s_add_i32 m0, s26, 0x2000
	s_add_i32 s24, s24, s25
	global_load_lds_dwordx4 v[218:219], off
	s_mov_b32 m0, s24
	s_nop 0
	global_load_lds_dwordx4 v[236:237], off
	s_add_i32 m0, s24, 0x2000
	s_nop 0
	global_load_lds_dwordx4 v[238:239], off
	s_waitcnt vmcnt(6)
	s_waitcnt lgkmcnt(0)
	s_barrier
; #define PG8_STAGE(bufoff, gbase, voff) do { _Pragma("unroll") for (int _i = 0; _i < 2; ++_i) \
;         __builtin_amdgcn_global_load_lds((const unsigned*)((const char*)(gbase) + (voff)[_i]), (LAS unsigned*)(lds + (bufoff) + ldsw + _i * 8192), 16, 0, 0); } while (0)
; #define PG8_LDA(dst, b, h) do { _Pragma("unroll") for (int m = 0; m < 4; ++m) _Pragma("unroll") for (int k = 0; k < 2; ++k) dst[m][k] = *(const LAS bf16x8*)(lds + PG8_SA(b, h) + aoff + m * 2048 + k * 1024); } while (0)
; #define PG8_LDB(dst, b, h) do { _Pragma("unroll") for (int n = 0; n < 2; ++n) _Pragma("unroll") for (int k = 0; k < 2; ++k) dst[n][k] = *(const LAS bf16x8*)(lds + PG8_SB(b, h) + boff + n * 2048 + k * 1024); } while (0)
; #define PG8_MMA(ai, bj, At, Bt) do { __builtin_amdgcn_s_setprio(1); _Pragma("unroll") for (int m = 0; m < 4; ++m) _Pragma("unroll") for (int n = 0; n < 2; ++n) _Pragma("unroll") for (int k = 0; k < 2; ++k) \
;         acc[ai][bj][m][n] = __builtin_amdgcn_mfma_f32_16x16x32_bf16(Bt[n][k], At[m][k], acc[ai][bj][m][n], 0, 0, 0); __builtin_amdgcn_s_setprio(0); } while (0)
; #define PG8_WAIT_V(n) asm volatile("s_waitcnt vmcnt(" #n ")" ::: "memory")
; #define PG8_WAIT_L(n) asm volatile("s_waitcnt lgkmcnt(" #n ")" ::: "memory")
; #define PG8_BAR __builtin_amdgcn_s_barrier()
; #define PG8_SCHED __builtin_amdgcn_sched_barrier(0)
; template <class Epi, class Sched>
; __device__ __forceinline__ void gemm_phase(LAS unsigned char* lds, const Gemm g, const Sched& S, const Epi& E, const int tid) {
;     ...
;             PG8_WAIT_V(8); PG8_WAIT_L(0); PG8_BAR; PG8_MMA(1, 0, At, B0); PG8_MMA(1, 1, At, B1); PG8_BAR; PG8_SCHED;
;             PG8_LDB(B0, 1, 0); PG8_LDB(B1, 1, 1); PG8_SCHED; PG8_LDA(At, 1, 0); PG8_STAGE(PG8_SA(0, 1), a2 + hstepA, voffA);
;             PG8_WAIT_V(8); PG8_WAIT_L(0); PG8_BAR; PG8_MMA(0, 0, At, B0); PG8_MMA(0, 1, At, B1); PG8_BAR; PG8_SCHED;
	s_waitcnt lgkmcnt(0)
	v_mfma_f32_16x16x32_bf16 v[60:63], v[128:131], v[176:179], v[60:63]
	v_mfma_f32_16x16x32_bf16 v[56:59], v[136:139], v[176:179], v[56:59]
	v_mfma_f32_16x16x32_bf16 v[44:47], v[128:131], v[184:187], v[44:47]
	v_mfma_f32_16x16x32_bf16 v[40:43], v[136:139], v[184:187], v[40:43]
	v_mfma_f32_16x16x32_bf16 v[28:31], v[128:131], v[202:205], v[28:31]
	v_mfma_f32_16x16x32_bf16 v[24:27], v[136:139], v[202:205], v[24:27]
	v_mfma_f32_16x16x32_bf16 v[12:15], v[128:131], v[210:213], v[12:15]
	v_mfma_f32_16x16x32_bf16 v[8:11], v[136:139], v[210:213], v[8:11]
	s_mov_b32 m0, s45
	v_mfma_f32_16x16x32_bf16 v[60:63], v[132:135], v[180:183], v[60:63]
	global_load_lds_dwordx4 v[220:221], off
	v_mfma_f32_16x16x32_bf16 v[56:59], v[140:143], v[180:183], v[56:59]
	v_mfma_f32_16x16x32_bf16 v[44:47], v[132:135], v[188:191], v[44:47]
	v_mfma_f32_16x16x32_bf16 v[40:43], v[140:143], v[188:191], v[40:43]
	v_mfma_f32_16x16x32_bf16 v[28:31], v[132:135], v[206:209], v[28:31]
	v_mfma_f32_16x16x32_bf16 v[24:27], v[140:143], v[206:209], v[24:27]
	v_mfma_f32_16x16x32_bf16 v[12:15], v[132:135], v[214:217], v[12:15]
	v_mfma_f32_16x16x32_bf16 v[8:11], v[140:143], v[214:217], v[8:11]
	v_mfma_f32_16x16x32_bf16 v[52:55], v[160:163], v[176:179], v[52:55]
	v_mfma_f32_16x16x32_bf16 v[48:51], v[168:171], v[176:179], v[48:51]
	v_mfma_f32_16x16x32_bf16 v[36:39], v[160:163], v[184:187], v[36:39]
	v_mfma_f32_16x16x32_bf16 v[32:35], v[168:171], v[184:187], v[32:35]
	v_mfma_f32_16x16x32_bf16 v[20:23], v[160:163], v[202:205], v[20:23]
	v_mfma_f32_16x16x32_bf16 v[16:19], v[168:171], v[202:205], v[16:19]
	s_mov_b32 m0, s47
	v_mfma_f32_16x16x32_bf16 v[4:7], v[160:163], v[210:213], v[4:7]
	global_load_lds_dwordx4 v[222:223], off
	v_mfma_f32_16x16x32_bf16 v[0:3], v[168:171], v[210:213], v[0:3]
	v_mfma_f32_16x16x32_bf16 v[52:55], v[164:167], v[180:183], v[52:55]
	v_mfma_f32_16x16x32_bf16 v[48:51], v[172:175], v[180:183], v[48:51]
	v_mfma_f32_16x16x32_bf16 v[36:39], v[164:167], v[188:191], v[36:39]
	v_mfma_f32_16x16x32_bf16 v[32:35], v[172:175], v[188:191], v[32:35]
	v_mfma_f32_16x16x32_bf16 v[20:23], v[164:167], v[206:209], v[20:23]
	v_mfma_f32_16x16x32_bf16 v[16:19], v[172:175], v[206:209], v[16:19]
	v_mfma_f32_16x16x32_bf16 v[4:7], v[164:167], v[214:217], v[4:7]
	v_mfma_f32_16x16x32_bf16 v[0:3], v[172:175], v[214:217], v[0:3]
	s_barrier
	s_add_i32 s24, 0, 0x18000
	s_add_i32 s26, 0, 0x1c000
	v_add_u32_e32 v140, s24, v158
	v_add_u32_e32 v172, s26, v158
	ds_read_b128 v[128:131], v140
	ds_read_b128 v[132:135], v140 offset:1024
	ds_read_b128 v[136:139], v140 offset:2048
	ds_read_b128 v[140:143], v140 offset:3072
	ds_read_b128 v[160:163], v172
	ds_read_b128 v[164:167], v172 offset:1024
	ds_read_b128 v[168:171], v172 offset:2048
	ds_read_b128 v[172:175], v172 offset:3072
	s_add_u32 s48, s48, 0x80000
	s_addc_u32 s49, s49, 0
	s_mov_b32 m0, s52
	v_lshl_add_u64 v[234:235], s[48:49], 0, v[144:145]
	ds_read_b128 v[176:179], v159 offset:32768
	ds_read_b128 v[180:183], v159 offset:33792
	ds_read_b128 v[184:187], v159 offset:34816
	ds_read_b128 v[188:191], v159 offset:35840
	ds_read_b128 v[202:205], v159 offset:36864
	ds_read_b128 v[206:209], v159 offset:37888
	ds_read_b128 v[210:213], v159 offset:38912
	ds_read_b128 v[214:217], v159 offset:39936
	global_load_lds_dwordx4 v[234:235], off
	v_lshl_add_u64 v[234:235], s[48:49], 0, v[146:147]
	s_mov_b32 m0, s53
	s_nop 0
	global_load_lds_dwordx4 v[234:235], off
	s_waitcnt vmcnt(8)
	s_waitcnt lgkmcnt(0)
	s_barrier
; #define PG8_STAGE(bufoff, gbase, voff) do { _Pragma("unroll") for (int _i = 0; _i < 2; ++_i) \
;         __builtin_amdgcn_global_load_lds((const unsigned*)((const char*)(gbase) + (voff)[_i]), (LAS unsigned*)(lds + (bufoff) + ldsw + _i * 8192), 16, 0, 0); } while (0)
; #define PG8_LDA(dst, b, h) do { _Pragma("unroll") for (int m = 0; m < 4; ++m) _Pragma("unroll") for (int k = 0; k < 2; ++k) dst[m][k] = *(const LAS bf16x8*)(lds + PG8_SA(b, h) + aoff + m * 2048 + k * 1024); } while (0)
; #define PG8_MMA(ai, bj, At, Bt) do { __builtin_amdgcn_s_setprio(1); _Pragma("unroll") for (int m = 0; m < 4; ++m) _Pragma("unroll") for (int n = 0; n < 2; ++n) _Pragma("unroll") for (int k = 0; k < 2; ++k) \
;         acc[ai][bj][m][n] = __builtin_amdgcn_mfma_f32_16x16x32_bf16(Bt[n][k], At[m][k], acc[ai][bj][m][n], 0, 0, 0); __builtin_amdgcn_s_setprio(0); } while (0)
; #define PG8_WAIT_V(n) asm volatile("s_waitcnt vmcnt(" #n ")" ::: "memory")
; #define PG8_WAIT_L(n) asm volatile("s_waitcnt lgkmcnt(" #n ")" ::: "memory")
; #define PG8_BAR __builtin_amdgcn_s_barrier()
; #define PG8_SCHED __builtin_amdgcn_sched_barrier(0)
; template <class Epi, class Sched>
; __device__ __forceinline__ void gemm_phase(LAS unsigned char* lds, const Gemm g, const Sched& S, const Epi& E, const int tid) {
;     ...
;             PG8_WAIT_V(8); PG8_WAIT_L(0); PG8_BAR; PG8_MMA(0, 0, At, B0); PG8_MMA(0, 1, At, B1); PG8_BAR; PG8_SCHED;
;             PG8_LDA(At, 1, 1); PG8_STAGE(PG8_SB(1, 0), b3, voffB); PG8_STAGE(PG8_SB(1, 1), b3 + hstepB, voffB); PG8_STAGE(PG8_SA(1, 0), a3, voffA);
;             PG8_WAIT_V(8); PG8_WAIT_L(0); PG8_BAR; PG8_MMA(1, 0, At, B0); PG8_MMA(1, 1, At, B1); PG8_BAR; PG8_SCHED;
;         }
	s_waitcnt lgkmcnt(0)
	v_mfma_f32_16x16x32_bf16 v[124:127], v[128:131], v[176:179], v[124:127]
	v_mfma_f32_16x16x32_bf16 v[120:123], v[136:139], v[176:179], v[120:123]
	v_mfma_f32_16x16x32_bf16 v[108:111], v[128:131], v[184:187], v[108:111]
	v_lshl_add_u64 v[154:155], v[154:155], 0, s[34:35]
	v_mfma_f32_16x16x32_bf16 v[104:107], v[136:139], v[184:187], v[104:107]
	v_mfma_f32_16x16x32_bf16 v[92:95], v[128:131], v[202:205], v[92:95]
	v_mfma_f32_16x16x32_bf16 v[88:91], v[136:139], v[202:205], v[88:91]
	s_add_u32 s38, s38, 0x80080
	s_addc_u32 s39, s39, 0
	v_mfma_f32_16x16x32_bf16 v[76:79], v[128:131], v[210:213], v[76:79]
	v_mfma_f32_16x16x32_bf16 v[72:75], v[136:139], v[210:213], v[72:75]
	v_mfma_f32_16x16x32_bf16 v[124:127], v[132:135], v[180:183], v[124:127]
	v_lshl_add_u64 v[240:241], v[218:219], 0, s[34:35]
	v_mfma_f32_16x16x32_bf16 v[120:123], v[140:143], v[180:183], v[120:123]
	v_mfma_f32_16x16x32_bf16 v[108:111], v[132:135], v[188:191], v[108:111]
	v_mfma_f32_16x16x32_bf16 v[104:107], v[140:143], v[188:191], v[104:107]
	v_mfma_f32_16x16x32_bf16 v[92:95], v[132:135], v[206:209], v[92:95]
	v_lshl_add_u64 v[242:243], s[38:39], 0, v[192:193]
	v_mfma_f32_16x16x32_bf16 v[88:91], v[140:143], v[206:209], v[88:91]
	v_mfma_f32_16x16x32_bf16 v[76:79], v[132:135], v[214:217], v[76:79]
	v_mfma_f32_16x16x32_bf16 v[72:75], v[140:143], v[214:217], v[72:75]
	v_mfma_f32_16x16x32_bf16 v[116:119], v[160:163], v[176:179], v[116:119]
	v_mfma_f32_16x16x32_bf16 v[112:115], v[168:171], v[176:179], v[112:115]
	v_lshl_add_u64 v[244:245], s[38:39], 0, v[148:149]
	v_mfma_f32_16x16x32_bf16 v[100:103], v[160:163], v[184:187], v[100:103]
	v_mfma_f32_16x16x32_bf16 v[96:99], v[168:171], v[184:187], v[96:99]
	v_mfma_f32_16x16x32_bf16 v[84:87], v[160:163], v[202:205], v[84:87]
	v_mfma_f32_16x16x32_bf16 v[80:83], v[168:171], v[202:205], v[80:83]
	v_lshl_add_u64 v[246:247], v[220:221], 0, s[34:35]
	v_mfma_f32_16x16x32_bf16 v[68:71], v[160:163], v[210:213], v[68:71]
	v_mfma_f32_16x16x32_bf16 v[64:67], v[168:171], v[210:213], v[64:67]
	v_mfma_f32_16x16x32_bf16 v[116:119], v[164:167], v[180:183], v[116:119]
	v_mfma_f32_16x16x32_bf16 v[112:115], v[172:175], v[180:183], v[112:115]
	v_lshl_add_u64 v[248:249], v[222:223], 0, s[34:35]
	v_mfma_f32_16x16x32_bf16 v[100:103], v[164:167], v[188:191], v[100:103]
	v_mfma_f32_16x16x32_bf16 v[96:99], v[172:175], v[188:191], v[96:99]
	v_mfma_f32_16x16x32_bf16 v[84:87], v[164:167], v[206:209], v[84:87]
	v_mfma_f32_16x16x32_bf16 v[80:83], v[172:175], v[206:209], v[80:83]
	v_mfma_f32_16x16x32_bf16 v[68:71], v[164:167], v[214:217], v[68:71]
	v_mfma_f32_16x16x32_bf16 v[64:67], v[172:175], v[214:217], v[64:67]
	s_barrier
	s_add_i32 s24, s24, s25
	s_mov_b32 m0, s24
	ds_read_b128 v[176:179], v159 offset:49152
	ds_read_b128 v[180:183], v159 offset:50176
	ds_read_b128 v[184:187], v159 offset:51200
	ds_read_b128 v[188:191], v159 offset:52224
	ds_read_b128 v[202:205], v159 offset:53248
	ds_read_b128 v[206:209], v159 offset:54272
	ds_read_b128 v[210:213], v159 offset:55296
	ds_read_b128 v[214:217], v159 offset:56320
	global_load_lds_dwordx4 v[154:155], off
	s_add_i32 m0, s24, 0x2000
	s_add_i32 s24, s26, s25
	global_load_lds_dwordx4 v[240:241], off
	s_mov_b32 m0, s24
	s_nop 0
	global_load_lds_dwordx4 v[242:243], off
	s_add_i32 m0, s24, 0x2000
	s_nop 0
	global_load_lds_dwordx4 v[244:245], off
	s_waitcnt vmcnt(6)
	s_waitcnt lgkmcnt(0)
	s_barrier
	s_waitcnt lgkmcnt(0)
	v_mfma_f32_16x16x32_bf16 v[60:63], v[128:131], v[176:179], v[60:63]
	v_mfma_f32_16x16x32_bf16 v[56:59], v[136:139], v[176:179], v[56:59]
	v_mfma_f32_16x16x32_bf16 v[44:47], v[128:131], v[184:187], v[44:47]
	v_mfma_f32_16x16x32_bf16 v[40:43], v[136:139], v[184:187], v[40:43]
	v_mfma_f32_16x16x32_bf16 v[28:31], v[128:131], v[202:205], v[28:31]
	v_mfma_f32_16x16x32_bf16 v[24:27], v[136:139], v[202:205], v[24:27]
	v_mfma_f32_16x16x32_bf16 v[12:15], v[128:131], v[210:213], v[12:15]
	v_mfma_f32_16x16x32_bf16 v[8:11], v[136:139], v[210:213], v[8:11]
	s_mov_b32 m0, s56
	v_mfma_f32_16x16x32_bf16 v[60:63], v[132:135], v[180:183], v[60:63]
	global_load_lds_dwordx4 v[246:247], off
	v_mfma_f32_16x16x32_bf16 v[56:59], v[140:143], v[180:183], v[56:59]
	v_mfma_f32_16x16x32_bf16 v[44:47], v[132:135], v[188:191], v[44:47]
	v_mfma_f32_16x16x32_bf16 v[40:43], v[140:143], v[188:191], v[40:43]
	v_mfma_f32_16x16x32_bf16 v[28:31], v[132:135], v[206:209], v[28:31]
	v_mfma_f32_16x16x32_bf16 v[24:27], v[140:143], v[206:209], v[24:27]
	v_mfma_f32_16x16x32_bf16 v[12:15], v[132:135], v[214:217], v[12:15]
	v_mfma_f32_16x16x32_bf16 v[8:11], v[140:143], v[214:217], v[8:11]
	v_mfma_f32_16x16x32_bf16 v[52:55], v[160:163], v[176:179], v[52:55]
	v_mfma_f32_16x16x32_bf16 v[48:51], v[168:171], v[176:179], v[48:51]
	v_mfma_f32_16x16x32_bf16 v[36:39], v[160:163], v[184:187], v[36:39]
	v_mfma_f32_16x16x32_bf16 v[32:35], v[168:171], v[184:187], v[32:35]
	v_mfma_f32_16x16x32_bf16 v[20:23], v[160:163], v[202:205], v[20:23]
	v_mfma_f32_16x16x32_bf16 v[16:19], v[168:171], v[202:205], v[16:19]
	s_mov_b32 m0, s57
	v_mfma_f32_16x16x32_bf16 v[4:7], v[160:163], v[210:213], v[4:7]
	global_load_lds_dwordx4 v[248:249], off
	v_mfma_f32_16x16x32_bf16 v[0:3], v[168:171], v[210:213], v[0:3]
	v_mfma_f32_16x16x32_bf16 v[52:55], v[164:167], v[180:183], v[52:55]
	v_mfma_f32_16x16x32_bf16 v[48:51], v[172:175], v[180:183], v[48:51]
	v_mfma_f32_16x16x32_bf16 v[36:39], v[164:167], v[188:191], v[36:39]
	v_mfma_f32_16x16x32_bf16 v[32:35], v[172:175], v[188:191], v[32:35]
	v_mfma_f32_16x16x32_bf16 v[20:23], v[164:167], v[206:209], v[20:23]
	v_mfma_f32_16x16x32_bf16 v[16:19], v[172:175], v[206:209], v[16:19]
	v_mfma_f32_16x16x32_bf16 v[4:7], v[164:167], v[214:217], v[4:7]
	v_mfma_f32_16x16x32_bf16 v[0:3], v[172:175], v[214:217], v[0:3]
	s_barrier
	s_add_i32 s22, s22, 2
	s_add_u32 s2, s2, 0x100
	s_addc_u32 s3, s3, 0
	s_add_u32 s20, s20, 0x100
	s_addc_u32 s21, s21, 0
	s_cmp_gt_u32 s22, 29
	s_cbranch_scc0 .LBB0_347
	s_and_b64 vcc, exec, s[8:9]
	s_cbranch_vccz .LBB0_350
	s_barrier
